# code placement: the 8 GEMM K-loop heads aligned to 64 bytes (s_nop fill), on v51
# baseline (speedup 1.0000x reference)
.LBB0_247:
	s_ashr_i32 s45, s44, 31
	s_lshl_b64 s[20:21], s[44:45], 19
	s_add_u32 s50, s16, s20
	s_addc_u32 s51, s17, s21
	s_and_b64 s[20:21], s[48:49], exec
	s_cselect_b32 s33, s51, s55
	s_cselect_b32 s39, s50, s54
	s_ashr_i32 s47, s46, 31
	s_lshl_b64 s[20:21], s[46:47], 19
	v_readlane_b32 s26, v255, 29
	v_readlane_b32 s27, v255, 30
	s_add_u32 s52, s26, s20
	s_addc_u32 s53, s27, s21
	s_and_b64 s[20:21], s[48:49], exec
	s_cselect_b32 s45, s53, s57
	s_cselect_b32 s47, s52, s56
	s_add_u32 s54, s54, 0x40080
	s_addc_u32 s55, s55, 0
	s_add_u32 s66, s56, 0x100
	v_mov_b32_e32 v0, 0
	s_addc_u32 s67, s57, 0
	s_mov_b32 s68, -2
	v_mov_b32_e32 v1, v0
	v_mov_b32_e32 v2, v0
	v_mov_b32_e32 v3, v0
	v_mov_b32_e32 v4, v0
	v_mov_b32_e32 v5, v0
	v_mov_b32_e32 v6, v0
	v_mov_b32_e32 v7, v0
	v_mov_b32_e32 v16, v0
	v_mov_b32_e32 v17, v0
	v_mov_b32_e32 v18, v0
	v_mov_b32_e32 v19, v0
	v_mov_b32_e32 v20, v0
	v_mov_b32_e32 v21, v0
	v_mov_b32_e32 v22, v0
	v_mov_b32_e32 v23, v0
	v_mov_b32_e32 v32, v0
	v_mov_b32_e32 v33, v0
	v_mov_b32_e32 v34, v0
	v_mov_b32_e32 v35, v0
	v_mov_b32_e32 v36, v0
	v_mov_b32_e32 v37, v0
	v_mov_b32_e32 v38, v0
	v_mov_b32_e32 v39, v0
	v_mov_b32_e32 v50, v0
	v_mov_b32_e32 v51, v0
	v_mov_b32_e32 v52, v0
	v_mov_b32_e32 v53, v0
	v_mov_b32_e32 v54, v0
	v_mov_b32_e32 v55, v0
	v_mov_b32_e32 v56, v0
	v_mov_b32_e32 v57, v0
	v_mov_b32_e32 v8, v0
	v_mov_b32_e32 v9, v0
	v_mov_b32_e32 v10, v0
	v_mov_b32_e32 v11, v0
	v_mov_b32_e32 v12, v0
	v_mov_b32_e32 v13, v0
	v_mov_b32_e32 v14, v0
	v_mov_b32_e32 v15, v0
	v_mov_b32_e32 v24, v0
	v_mov_b32_e32 v25, v0
	v_mov_b32_e32 v26, v0
	v_mov_b32_e32 v27, v0
	v_mov_b32_e32 v28, v0
	v_mov_b32_e32 v29, v0
	v_mov_b32_e32 v30, v0
	v_mov_b32_e32 v31, v0
	v_mov_b32_e32 v40, v0
	v_mov_b32_e32 v41, v0
	v_mov_b32_e32 v42, v0
	v_mov_b32_e32 v43, v0
	v_mov_b32_e32 v44, v0
	v_mov_b32_e32 v45, v0
	v_mov_b32_e32 v46, v0
	v_mov_b32_e32 v47, v0
	v_mov_b32_e32 v58, v0
	v_mov_b32_e32 v59, v0
	v_mov_b32_e32 v60, v0
	v_mov_b32_e32 v61, v0
	v_mov_b32_e32 v62, v0
	v_mov_b32_e32 v63, v0
	v_mov_b32_e32 v64, v0
	v_mov_b32_e32 v65, v0
	v_mov_b32_e32 v66, v0
	v_mov_b32_e32 v67, v0
	v_mov_b32_e32 v68, v0
	v_mov_b32_e32 v69, v0
	v_mov_b32_e32 v70, v0
	v_mov_b32_e32 v71, v0
	v_mov_b32_e32 v72, v0
	v_mov_b32_e32 v73, v0
	v_mov_b32_e32 v82, v0
	v_mov_b32_e32 v83, v0
	v_mov_b32_e32 v84, v0
	v_mov_b32_e32 v85, v0
	v_mov_b32_e32 v86, v0
	v_mov_b32_e32 v87, v0
	v_mov_b32_e32 v88, v0
	v_mov_b32_e32 v89, v0
	v_mov_b32_e32 v98, v0
	v_mov_b32_e32 v99, v0
	v_mov_b32_e32 v100, v0
	v_mov_b32_e32 v101, v0
	v_mov_b32_e32 v102, v0
	v_mov_b32_e32 v103, v0
	v_mov_b32_e32 v104, v0
	v_mov_b32_e32 v105, v0
	v_mov_b32_e32 v114, v0
	v_mov_b32_e32 v115, v0
	v_mov_b32_e32 v116, v0
	v_mov_b32_e32 v117, v0
	v_mov_b32_e32 v118, v0
	v_mov_b32_e32 v119, v0
	v_mov_b32_e32 v120, v0
	v_mov_b32_e32 v121, v0
	v_mov_b32_e32 v74, v0
	v_mov_b32_e32 v75, v0
	v_mov_b32_e32 v76, v0
	v_mov_b32_e32 v77, v0
	v_mov_b32_e32 v78, v0
	v_mov_b32_e32 v79, v0
	v_mov_b32_e32 v80, v0
	v_mov_b32_e32 v81, v0
	v_mov_b32_e32 v90, v0
	v_mov_b32_e32 v91, v0
	v_mov_b32_e32 v92, v0
	v_mov_b32_e32 v93, v0
	v_mov_b32_e32 v94, v0
	v_mov_b32_e32 v95, v0
	v_mov_b32_e32 v96, v0
	v_mov_b32_e32 v97, v0
	v_mov_b32_e32 v106, v0
	v_mov_b32_e32 v107, v0
	v_mov_b32_e32 v108, v0
	v_mov_b32_e32 v109, v0
	v_mov_b32_e32 v110, v0
	v_mov_b32_e32 v111, v0
	v_mov_b32_e32 v112, v0
	v_mov_b32_e32 v113, v0
	v_mov_b32_e32 v122, v0
	v_mov_b32_e32 v123, v0
	v_mov_b32_e32 v124, v0
	v_mov_b32_e32 v125, v0
	v_mov_b32_e32 v126, v0
	v_mov_b32_e32 v127, v0
	v_mov_b32_e32 v128, v0
	v_mov_b32_e32 v129, v0
	.p2alignl 6, 3212836864

.LBB0_471:
	s_add_u32 s69, s52, 0x100
	v_mov_b32_e32 v0, 0
	s_addc_u32 s70, s53, 0
	s_mov_b32 s71, -2
	v_mov_b32_e32 v1, v0
	v_mov_b32_e32 v2, v0
	v_mov_b32_e32 v3, v0
	v_mov_b32_e32 v4, v0
	v_mov_b32_e32 v5, v0
	v_mov_b32_e32 v6, v0
	v_mov_b32_e32 v7, v0
	v_mov_b32_e32 v16, v0
	v_mov_b32_e32 v17, v0
	v_mov_b32_e32 v18, v0
	v_mov_b32_e32 v19, v0
	v_mov_b32_e32 v20, v0
	v_mov_b32_e32 v21, v0
	v_mov_b32_e32 v22, v0
	v_mov_b32_e32 v23, v0
	v_mov_b32_e32 v32, v0
	v_mov_b32_e32 v33, v0
	v_mov_b32_e32 v34, v0
	v_mov_b32_e32 v35, v0
	v_mov_b32_e32 v36, v0
	v_mov_b32_e32 v37, v0
	v_mov_b32_e32 v38, v0
	v_mov_b32_e32 v39, v0
	v_mov_b32_e32 v50, v0
	v_mov_b32_e32 v51, v0
	v_mov_b32_e32 v52, v0
	v_mov_b32_e32 v53, v0
	v_mov_b32_e32 v54, v0
	v_mov_b32_e32 v55, v0
	v_mov_b32_e32 v56, v0
	v_mov_b32_e32 v57, v0
	v_mov_b32_e32 v8, v0
	v_mov_b32_e32 v9, v0
	v_mov_b32_e32 v10, v0
	v_mov_b32_e32 v11, v0
	v_mov_b32_e32 v12, v0
	v_mov_b32_e32 v13, v0
	v_mov_b32_e32 v14, v0
	v_mov_b32_e32 v15, v0
	v_mov_b32_e32 v24, v0
	v_mov_b32_e32 v25, v0
	v_mov_b32_e32 v26, v0
	v_mov_b32_e32 v27, v0
	v_mov_b32_e32 v28, v0
	v_mov_b32_e32 v29, v0
	v_mov_b32_e32 v30, v0
	v_mov_b32_e32 v31, v0
	v_mov_b32_e32 v40, v0
	v_mov_b32_e32 v41, v0
	v_mov_b32_e32 v42, v0
	v_mov_b32_e32 v43, v0
	v_mov_b32_e32 v44, v0
	v_mov_b32_e32 v45, v0
	v_mov_b32_e32 v46, v0
	v_mov_b32_e32 v47, v0
	v_mov_b32_e32 v58, v0
	v_mov_b32_e32 v59, v0
	v_mov_b32_e32 v60, v0
	v_mov_b32_e32 v61, v0
	v_mov_b32_e32 v62, v0
	v_mov_b32_e32 v63, v0
	v_mov_b32_e32 v64, v0
	v_mov_b32_e32 v65, v0
	v_mov_b32_e32 v66, v0
	v_mov_b32_e32 v67, v0
	v_mov_b32_e32 v68, v0
	v_mov_b32_e32 v69, v0
	v_mov_b32_e32 v70, v0
	v_mov_b32_e32 v71, v0
	v_mov_b32_e32 v72, v0
	v_mov_b32_e32 v73, v0
	v_mov_b32_e32 v82, v0
	v_mov_b32_e32 v83, v0
	v_mov_b32_e32 v84, v0
	v_mov_b32_e32 v85, v0
	v_mov_b32_e32 v86, v0
	v_mov_b32_e32 v87, v0
	v_mov_b32_e32 v88, v0
	v_mov_b32_e32 v89, v0
	v_mov_b32_e32 v98, v0
	v_mov_b32_e32 v99, v0
	v_mov_b32_e32 v100, v0
	v_mov_b32_e32 v101, v0
	v_mov_b32_e32 v102, v0
	v_mov_b32_e32 v103, v0
	v_mov_b32_e32 v104, v0
	v_mov_b32_e32 v105, v0
	v_mov_b32_e32 v114, v0
	v_mov_b32_e32 v115, v0
	v_mov_b32_e32 v116, v0
	v_mov_b32_e32 v117, v0
	v_mov_b32_e32 v118, v0
	v_mov_b32_e32 v119, v0
	v_mov_b32_e32 v120, v0
	v_mov_b32_e32 v121, v0
	v_mov_b32_e32 v74, v0
	v_mov_b32_e32 v75, v0
	v_mov_b32_e32 v76, v0
	v_mov_b32_e32 v77, v0
	v_mov_b32_e32 v78, v0
	v_mov_b32_e32 v79, v0
	v_mov_b32_e32 v80, v0
	v_mov_b32_e32 v81, v0
	v_mov_b32_e32 v90, v0
	v_mov_b32_e32 v91, v0
	v_mov_b32_e32 v92, v0
	v_mov_b32_e32 v93, v0
	v_mov_b32_e32 v94, v0
	v_mov_b32_e32 v95, v0
	v_mov_b32_e32 v96, v0
	v_mov_b32_e32 v97, v0
	v_mov_b32_e32 v106, v0
	v_mov_b32_e32 v107, v0
	v_mov_b32_e32 v108, v0
	v_mov_b32_e32 v109, v0
	v_mov_b32_e32 v110, v0
	v_mov_b32_e32 v111, v0
	v_mov_b32_e32 v112, v0
	v_mov_b32_e32 v113, v0
	v_mov_b32_e32 v126, v0
	v_mov_b32_e32 v127, v0
	v_mov_b32_e32 v128, v0
	v_mov_b32_e32 v129, v0
	v_mov_b32_e32 v134, v0
	v_mov_b32_e32 v135, v0
	v_mov_b32_e32 v136, v0
	v_mov_b32_e32 v137, v0
	.p2alignl 6, 3212836864

.LBB0_584:
	s_ashr_i32 s51, s50, 31
	s_lshl_b64 s[20:21], s[50:51], 19
	s_add_u32 s56, s16, s20
	s_addc_u32 s57, s17, s21
	s_and_b64 s[20:21], s[54:55], exec
	s_cselect_b32 s18, s57, s61
	s_cselect_b32 s33, s56, s60
	s_ashr_i32 s53, s52, 31
	s_lshl_b64 s[20:21], s[52:53], 19
	s_add_u32 s58, s8, s20
	s_addc_u32 s59, s9, s21
	s_and_b64 s[20:21], s[54:55], exec
	s_cselect_b32 s43, s59, s63
	s_cselect_b32 s45, s58, s62
	s_add_u32 s60, s60, 0x40080
	s_addc_u32 s61, s61, 0
	s_add_u32 s51, s62, 0x100
	v_mov_b32_e32 v0, 0
	s_addc_u32 s53, s63, 0
	s_mov_b32 s90, -2
	v_mov_b32_e32 v1, v0
	v_mov_b32_e32 v2, v0
	v_mov_b32_e32 v3, v0
	v_mov_b32_e32 v4, v0
	v_mov_b32_e32 v5, v0
	v_mov_b32_e32 v6, v0
	v_mov_b32_e32 v7, v0
	v_mov_b32_e32 v16, v0
	v_mov_b32_e32 v17, v0
	v_mov_b32_e32 v18, v0
	v_mov_b32_e32 v19, v0
	v_mov_b32_e32 v20, v0
	v_mov_b32_e32 v21, v0
	v_mov_b32_e32 v22, v0
	v_mov_b32_e32 v23, v0
	v_mov_b32_e32 v32, v0
	v_mov_b32_e32 v33, v0
	v_mov_b32_e32 v34, v0
	v_mov_b32_e32 v35, v0
	v_mov_b32_e32 v36, v0
	v_mov_b32_e32 v37, v0
	v_mov_b32_e32 v38, v0
	v_mov_b32_e32 v39, v0
	v_mov_b32_e32 v50, v0
	v_mov_b32_e32 v51, v0
	v_mov_b32_e32 v52, v0
	v_mov_b32_e32 v53, v0
	v_mov_b32_e32 v54, v0
	v_mov_b32_e32 v55, v0
	v_mov_b32_e32 v56, v0
	v_mov_b32_e32 v57, v0
	v_mov_b32_e32 v8, v0
	v_mov_b32_e32 v9, v0
	v_mov_b32_e32 v10, v0
	v_mov_b32_e32 v11, v0
	v_mov_b32_e32 v12, v0
	v_mov_b32_e32 v13, v0
	v_mov_b32_e32 v14, v0
	v_mov_b32_e32 v15, v0
	v_mov_b32_e32 v24, v0
	v_mov_b32_e32 v25, v0
	v_mov_b32_e32 v26, v0
	v_mov_b32_e32 v27, v0
	v_mov_b32_e32 v28, v0
	v_mov_b32_e32 v29, v0
	v_mov_b32_e32 v30, v0
	v_mov_b32_e32 v31, v0
	v_mov_b32_e32 v40, v0
	v_mov_b32_e32 v41, v0
	v_mov_b32_e32 v42, v0
	v_mov_b32_e32 v43, v0
	v_mov_b32_e32 v44, v0
	v_mov_b32_e32 v45, v0
	v_mov_b32_e32 v46, v0
	v_mov_b32_e32 v47, v0
	v_mov_b32_e32 v58, v0
	v_mov_b32_e32 v59, v0
	v_mov_b32_e32 v60, v0
	v_mov_b32_e32 v61, v0
	v_mov_b32_e32 v62, v0
	v_mov_b32_e32 v63, v0
	v_mov_b32_e32 v64, v0
	v_mov_b32_e32 v65, v0
	v_mov_b32_e32 v66, v0
	v_mov_b32_e32 v67, v0
	v_mov_b32_e32 v68, v0
	v_mov_b32_e32 v69, v0
	v_mov_b32_e32 v70, v0
	v_mov_b32_e32 v71, v0
	v_mov_b32_e32 v72, v0
	v_mov_b32_e32 v73, v0
	v_mov_b32_e32 v82, v0
	v_mov_b32_e32 v83, v0
	v_mov_b32_e32 v84, v0
	v_mov_b32_e32 v85, v0
	v_mov_b32_e32 v86, v0
	v_mov_b32_e32 v87, v0
	v_mov_b32_e32 v88, v0
	v_mov_b32_e32 v89, v0
	v_mov_b32_e32 v98, v0
	v_mov_b32_e32 v99, v0
	v_mov_b32_e32 v100, v0
	v_mov_b32_e32 v101, v0
	v_mov_b32_e32 v102, v0
	v_mov_b32_e32 v103, v0
	v_mov_b32_e32 v104, v0
	v_mov_b32_e32 v105, v0
	v_mov_b32_e32 v114, v0
	v_mov_b32_e32 v115, v0
	v_mov_b32_e32 v116, v0
	v_mov_b32_e32 v117, v0
	v_mov_b32_e32 v118, v0
	v_mov_b32_e32 v119, v0
	v_mov_b32_e32 v120, v0
	v_mov_b32_e32 v121, v0
	v_mov_b32_e32 v74, v0
	v_mov_b32_e32 v75, v0
	v_mov_b32_e32 v76, v0
	v_mov_b32_e32 v77, v0
	v_mov_b32_e32 v78, v0
	v_mov_b32_e32 v79, v0
	v_mov_b32_e32 v80, v0
	v_mov_b32_e32 v81, v0
	v_mov_b32_e32 v90, v0
	v_mov_b32_e32 v91, v0
	v_mov_b32_e32 v92, v0
	v_mov_b32_e32 v93, v0
	v_mov_b32_e32 v94, v0
	v_mov_b32_e32 v95, v0
	v_mov_b32_e32 v96, v0
	v_mov_b32_e32 v97, v0
	v_mov_b32_e32 v106, v0
	v_mov_b32_e32 v107, v0
	v_mov_b32_e32 v108, v0
	v_mov_b32_e32 v109, v0
	v_mov_b32_e32 v110, v0
	v_mov_b32_e32 v111, v0
	v_mov_b32_e32 v112, v0
	v_mov_b32_e32 v113, v0
	v_mov_b32_e32 v122, v0
	v_mov_b32_e32 v123, v0
	v_mov_b32_e32 v124, v0
	v_mov_b32_e32 v125, v0
	v_mov_b32_e32 v126, v0
	v_mov_b32_e32 v127, v0
	v_mov_b32_e32 v128, v0
	v_mov_b32_e32 v129, v0
	.p2alignl 6, 3212836864

.LBB0_689:
	s_ashr_i32 s47, s46, 31
	s_lshl_b64 s[20:21], s[46:47], 19
	s_add_u32 s52, s16, s20
	s_addc_u32 s53, s17, s21
	s_and_b64 s[20:21], s[50:51], exec
	s_cselect_b32 s41, s53, s57
	s_cselect_b32 s47, s52, s56
	s_ashr_i32 s49, s48, 31
	s_lshl_b64 s[20:21], s[48:49], 19
	s_add_u32 s54, s8, s20
	s_addc_u32 s55, s9, s21
	s_and_b64 s[20:21], s[50:51], exec
	s_cselect_b32 s49, s55, s59
	s_cselect_b32 s68, s54, s58
	s_add_u32 s56, s56, 0x40080
	s_addc_u32 s57, s57, 0
	s_add_u32 s69, s58, 0x100
	v_mov_b32_e32 v0, 0
	s_addc_u32 s70, s59, 0
	s_mov_b32 s71, -2
	v_mov_b32_e32 v1, v0
	v_mov_b32_e32 v2, v0
	v_mov_b32_e32 v3, v0
	v_mov_b32_e32 v4, v0
	v_mov_b32_e32 v5, v0
	v_mov_b32_e32 v6, v0
	v_mov_b32_e32 v7, v0
	v_mov_b32_e32 v8, v0
	v_mov_b32_e32 v9, v0
	v_mov_b32_e32 v10, v0
	v_mov_b32_e32 v11, v0
	v_mov_b32_e32 v16, v0
	v_mov_b32_e32 v17, v0
	v_mov_b32_e32 v18, v0
	v_mov_b32_e32 v19, v0
	v_mov_b32_e32 v24, v0
	v_mov_b32_e32 v25, v0
	v_mov_b32_e32 v26, v0
	v_mov_b32_e32 v27, v0
	v_mov_b32_e32 v32, v0
	v_mov_b32_e32 v33, v0
	v_mov_b32_e32 v34, v0
	v_mov_b32_e32 v35, v0
	v_mov_b32_e32 v40, v0
	v_mov_b32_e32 v41, v0
	v_mov_b32_e32 v42, v0
	v_mov_b32_e32 v43, v0
	v_mov_b32_e32 v50, v0
	v_mov_b32_e32 v51, v0
	v_mov_b32_e32 v52, v0
	v_mov_b32_e32 v53, v0
	v_mov_b32_e32 v12, v0
	v_mov_b32_e32 v13, v0
	v_mov_b32_e32 v14, v0
	v_mov_b32_e32 v15, v0
	v_mov_b32_e32 v20, v0
	v_mov_b32_e32 v21, v0
	v_mov_b32_e32 v22, v0
	v_mov_b32_e32 v23, v0
	v_mov_b32_e32 v28, v0
	v_mov_b32_e32 v29, v0
	v_mov_b32_e32 v30, v0
	v_mov_b32_e32 v31, v0
	v_mov_b32_e32 v36, v0
	v_mov_b32_e32 v37, v0
	v_mov_b32_e32 v38, v0
	v_mov_b32_e32 v39, v0
	v_mov_b32_e32 v44, v0
	v_mov_b32_e32 v45, v0
	v_mov_b32_e32 v46, v0
	v_mov_b32_e32 v47, v0
	v_mov_b32_e32 v54, v0
	v_mov_b32_e32 v55, v0
	v_mov_b32_e32 v56, v0
	v_mov_b32_e32 v57, v0
	v_mov_b32_e32 v58, v0
	v_mov_b32_e32 v59, v0
	v_mov_b32_e32 v60, v0
	v_mov_b32_e32 v61, v0
	v_mov_b32_e32 v62, v0
	v_mov_b32_e32 v63, v0
	v_mov_b32_e32 v64, v0
	v_mov_b32_e32 v65, v0
	v_mov_b32_e32 v66, v0
	v_mov_b32_e32 v67, v0
	v_mov_b32_e32 v68, v0
	v_mov_b32_e32 v69, v0
	v_mov_b32_e32 v70, v0
	v_mov_b32_e32 v71, v0
	v_mov_b32_e32 v72, v0
	v_mov_b32_e32 v73, v0
	v_mov_b32_e32 v74, v0
	v_mov_b32_e32 v75, v0
	v_mov_b32_e32 v76, v0
	v_mov_b32_e32 v77, v0
	v_mov_b32_e32 v82, v0
	v_mov_b32_e32 v83, v0
	v_mov_b32_e32 v84, v0
	v_mov_b32_e32 v85, v0
	v_mov_b32_e32 v90, v0
	v_mov_b32_e32 v91, v0
	v_mov_b32_e32 v92, v0
	v_mov_b32_e32 v93, v0
	v_mov_b32_e32 v98, v0
	v_mov_b32_e32 v99, v0
	v_mov_b32_e32 v100, v0
	v_mov_b32_e32 v101, v0
	v_mov_b32_e32 v106, v0
	v_mov_b32_e32 v107, v0
	v_mov_b32_e32 v108, v0
	v_mov_b32_e32 v109, v0
	v_mov_b32_e32 v114, v0
	v_mov_b32_e32 v115, v0
	v_mov_b32_e32 v116, v0
	v_mov_b32_e32 v117, v0
	v_mov_b32_e32 v78, v0
	v_mov_b32_e32 v79, v0
	v_mov_b32_e32 v80, v0
	v_mov_b32_e32 v81, v0
	v_mov_b32_e32 v86, v0
	v_mov_b32_e32 v87, v0
	v_mov_b32_e32 v88, v0
	v_mov_b32_e32 v89, v0
	v_mov_b32_e32 v94, v0
	v_mov_b32_e32 v95, v0
	v_mov_b32_e32 v96, v0
	v_mov_b32_e32 v97, v0
	v_mov_b32_e32 v102, v0
	v_mov_b32_e32 v103, v0
	v_mov_b32_e32 v104, v0
	v_mov_b32_e32 v105, v0
	v_mov_b32_e32 v110, v0
	v_mov_b32_e32 v111, v0
	v_mov_b32_e32 v112, v0
	v_mov_b32_e32 v113, v0
	v_mov_b32_e32 v118, v0
	v_mov_b32_e32 v119, v0
	v_mov_b32_e32 v120, v0
	v_mov_b32_e32 v121, v0
	v_mov_b32_e32 v122, v0
	v_mov_b32_e32 v123, v0
	v_mov_b32_e32 v124, v0
	v_mov_b32_e32 v125, v0
	v_mov_b32_e32 v126, v0
	v_mov_b32_e32 v127, v0
	v_mov_b32_e32 v128, v0
	v_mov_b32_e32 v129, v0
	.p2alignl 6, 3212836864

.LBB0_788:
	s_or_b64 exec, exec, s[42:43]
	v_lshl_add_u64 v[148:149], v[0:1], 0, s[34:35]
	v_mov_b32_e32 v0, 0
	s_mov_b32 s18, -2
	v_mov_b32_e32 v1, v0
	v_mov_b32_e32 v2, v0
	v_mov_b32_e32 v3, v0
	v_mov_b32_e32 v4, v0
	v_mov_b32_e32 v5, v0
	v_mov_b32_e32 v6, v0
	v_mov_b32_e32 v7, v0
	v_mov_b32_e32 v8, v0
	v_mov_b32_e32 v9, v0
	v_mov_b32_e32 v10, v0
	v_mov_b32_e32 v11, v0
	v_mov_b32_e32 v12, v0
	v_mov_b32_e32 v13, v0
	v_mov_b32_e32 v14, v0
	v_mov_b32_e32 v15, v0
	v_mov_b32_e32 v16, v0
	v_mov_b32_e32 v17, v0
	v_mov_b32_e32 v18, v0
	v_mov_b32_e32 v19, v0
	v_mov_b32_e32 v20, v0
	v_mov_b32_e32 v21, v0
	v_mov_b32_e32 v22, v0
	v_mov_b32_e32 v23, v0
	v_mov_b32_e32 v24, v0
	v_mov_b32_e32 v25, v0
	v_mov_b32_e32 v26, v0
	v_mov_b32_e32 v27, v0
	v_mov_b32_e32 v28, v0
	v_mov_b32_e32 v29, v0
	v_mov_b32_e32 v30, v0
	v_mov_b32_e32 v31, v0
	v_mov_b32_e32 v66, v0
	v_mov_b32_e32 v67, v0
	v_mov_b32_e32 v68, v0
	v_mov_b32_e32 v69, v0
	v_mov_b32_e32 v70, v0
	v_mov_b32_e32 v71, v0
	v_mov_b32_e32 v72, v0
	v_mov_b32_e32 v73, v0
	v_mov_b32_e32 v74, v0
	v_mov_b32_e32 v75, v0
	v_mov_b32_e32 v76, v0
	v_mov_b32_e32 v77, v0
	v_mov_b32_e32 v78, v0
	v_mov_b32_e32 v79, v0
	v_mov_b32_e32 v80, v0
	v_mov_b32_e32 v81, v0
	v_mov_b32_e32 v82, v0
	v_mov_b32_e32 v83, v0
	v_mov_b32_e32 v84, v0
	v_mov_b32_e32 v85, v0
	v_mov_b32_e32 v86, v0
	v_mov_b32_e32 v87, v0
	v_mov_b32_e32 v88, v0
	v_mov_b32_e32 v89, v0
	v_mov_b32_e32 v90, v0
	v_mov_b32_e32 v91, v0
	v_mov_b32_e32 v92, v0
	v_mov_b32_e32 v93, v0
	v_mov_b32_e32 v94, v0
	v_mov_b32_e32 v95, v0
	v_mov_b32_e32 v96, v0
	v_mov_b32_e32 v97, v0
	v_mov_b32_e32 v32, v0
	v_mov_b32_e32 v33, v0
	v_mov_b32_e32 v34, v0
	v_mov_b32_e32 v35, v0
	v_mov_b32_e32 v36, v0
	v_mov_b32_e32 v37, v0
	v_mov_b32_e32 v38, v0
	v_mov_b32_e32 v39, v0
	v_mov_b32_e32 v40, v0
	v_mov_b32_e32 v41, v0
	v_mov_b32_e32 v42, v0
	v_mov_b32_e32 v43, v0
	v_mov_b32_e32 v44, v0
	v_mov_b32_e32 v45, v0
	v_mov_b32_e32 v46, v0
	v_mov_b32_e32 v47, v0
	v_mov_b32_e32 v50, v0
	v_mov_b32_e32 v51, v0
	v_mov_b32_e32 v52, v0
	v_mov_b32_e32 v53, v0
	v_mov_b32_e32 v54, v0
	v_mov_b32_e32 v55, v0
	v_mov_b32_e32 v56, v0
	v_mov_b32_e32 v57, v0
	v_mov_b32_e32 v58, v0
	v_mov_b32_e32 v59, v0
	v_mov_b32_e32 v60, v0
	v_mov_b32_e32 v61, v0
	v_mov_b32_e32 v62, v0
	v_mov_b32_e32 v63, v0
	v_mov_b32_e32 v64, v0
	v_mov_b32_e32 v65, v0
	v_mov_b32_e32 v98, v0
	v_mov_b32_e32 v99, v0
	v_mov_b32_e32 v100, v0
	v_mov_b32_e32 v101, v0
	v_mov_b32_e32 v102, v0
	v_mov_b32_e32 v103, v0
	v_mov_b32_e32 v104, v0
	v_mov_b32_e32 v105, v0
	v_mov_b32_e32 v106, v0
	v_mov_b32_e32 v107, v0
	v_mov_b32_e32 v108, v0
	v_mov_b32_e32 v109, v0
	v_mov_b32_e32 v110, v0
	v_mov_b32_e32 v111, v0
	v_mov_b32_e32 v112, v0
	v_mov_b32_e32 v113, v0
	v_mov_b32_e32 v114, v0
	v_mov_b32_e32 v115, v0
	v_mov_b32_e32 v116, v0
	v_mov_b32_e32 v117, v0
	v_mov_b32_e32 v118, v0
	v_mov_b32_e32 v119, v0
	v_mov_b32_e32 v120, v0
	v_mov_b32_e32 v121, v0
	v_mov_b32_e32 v122, v0
	v_mov_b32_e32 v123, v0
	v_mov_b32_e32 v124, v0
	v_mov_b32_e32 v125, v0
	v_mov_b32_e32 v126, v0
	v_mov_b32_e32 v127, v0
	v_mov_b32_e32 v128, v0
	v_mov_b32_e32 v129, v0
	.p2alignl 6, 3212836864

.LBB0_1300:
	s_ashr_i32 s45, s44, 31
	s_lshl_b64 s[20:21], s[44:45], 19
	v_readlane_b32 s26, v255, 35
	v_readlane_b32 s27, v255, 36
	s_add_u32 s48, s26, s20
	s_addc_u32 s49, s27, s21
	s_and_b64 s[20:21], s[42:43], exec
	s_cselect_b32 s18, s49, s57
	s_cselect_b32 s33, s48, s56
	s_ashr_i32 s47, s46, 31
	s_lshl_b64 s[20:21], s[46:47], 19
	s_add_u32 s50, s8, s20
	s_addc_u32 s51, s9, s21
	s_and_b64 s[20:21], s[42:43], exec
	s_cselect_b32 s45, s51, s59
	s_cselect_b32 s47, s50, s58
	s_add_u32 s56, s56, 0x40080
	s_addc_u32 s57, s57, 0
	s_add_u32 s53, s58, 0x100
	v_mov_b32_e32 v0, 0
	s_addc_u32 s69, s59, 0
	s_mov_b32 s70, -2
	v_mov_b32_e32 v1, v0
	v_mov_b32_e32 v2, v0
	v_mov_b32_e32 v3, v0
	v_mov_b32_e32 v4, v0
	v_mov_b32_e32 v5, v0
	v_mov_b32_e32 v6, v0
	v_mov_b32_e32 v7, v0
	v_mov_b32_e32 v16, v0
	v_mov_b32_e32 v17, v0
	v_mov_b32_e32 v18, v0
	v_mov_b32_e32 v19, v0
	v_mov_b32_e32 v20, v0
	v_mov_b32_e32 v21, v0
	v_mov_b32_e32 v22, v0
	v_mov_b32_e32 v23, v0
	v_mov_b32_e32 v32, v0
	v_mov_b32_e32 v33, v0
	v_mov_b32_e32 v34, v0
	v_mov_b32_e32 v35, v0
	v_mov_b32_e32 v36, v0
	v_mov_b32_e32 v37, v0
	v_mov_b32_e32 v38, v0
	v_mov_b32_e32 v39, v0
	v_mov_b32_e32 v50, v0
	v_mov_b32_e32 v51, v0
	v_mov_b32_e32 v52, v0
	v_mov_b32_e32 v53, v0
	v_mov_b32_e32 v54, v0
	v_mov_b32_e32 v55, v0
	v_mov_b32_e32 v56, v0
	v_mov_b32_e32 v57, v0
	v_mov_b32_e32 v8, v0
	v_mov_b32_e32 v9, v0
	v_mov_b32_e32 v10, v0
	v_mov_b32_e32 v11, v0
	v_mov_b32_e32 v12, v0
	v_mov_b32_e32 v13, v0
	v_mov_b32_e32 v14, v0
	v_mov_b32_e32 v15, v0
	v_mov_b32_e32 v24, v0
	v_mov_b32_e32 v25, v0
	v_mov_b32_e32 v26, v0
	v_mov_b32_e32 v27, v0
	v_mov_b32_e32 v28, v0
	v_mov_b32_e32 v29, v0
	v_mov_b32_e32 v30, v0
	v_mov_b32_e32 v31, v0
	v_mov_b32_e32 v40, v0
	v_mov_b32_e32 v41, v0
	v_mov_b32_e32 v42, v0
	v_mov_b32_e32 v43, v0
	v_mov_b32_e32 v44, v0
	v_mov_b32_e32 v45, v0
	v_mov_b32_e32 v46, v0
	v_mov_b32_e32 v47, v0
	v_mov_b32_e32 v58, v0
	v_mov_b32_e32 v59, v0
	v_mov_b32_e32 v60, v0
	v_mov_b32_e32 v61, v0
	v_mov_b32_e32 v62, v0
	v_mov_b32_e32 v63, v0
	v_mov_b32_e32 v64, v0
	v_mov_b32_e32 v65, v0
	v_mov_b32_e32 v66, v0
	v_mov_b32_e32 v67, v0
	v_mov_b32_e32 v68, v0
	v_mov_b32_e32 v69, v0
	v_mov_b32_e32 v70, v0
	v_mov_b32_e32 v71, v0
	v_mov_b32_e32 v72, v0
	v_mov_b32_e32 v73, v0
	v_mov_b32_e32 v82, v0
	v_mov_b32_e32 v83, v0
	v_mov_b32_e32 v84, v0
	v_mov_b32_e32 v85, v0
	v_mov_b32_e32 v86, v0
	v_mov_b32_e32 v87, v0
	v_mov_b32_e32 v88, v0
	v_mov_b32_e32 v89, v0
	v_mov_b32_e32 v98, v0
	v_mov_b32_e32 v99, v0
	v_mov_b32_e32 v100, v0
	v_mov_b32_e32 v101, v0
	v_mov_b32_e32 v102, v0
	v_mov_b32_e32 v103, v0
	v_mov_b32_e32 v104, v0
	v_mov_b32_e32 v105, v0
	v_mov_b32_e32 v114, v0
	v_mov_b32_e32 v115, v0
	v_mov_b32_e32 v116, v0
	v_mov_b32_e32 v117, v0
	v_mov_b32_e32 v118, v0
	v_mov_b32_e32 v119, v0
	v_mov_b32_e32 v120, v0
	v_mov_b32_e32 v121, v0
	v_mov_b32_e32 v74, v0
	v_mov_b32_e32 v75, v0
	v_mov_b32_e32 v76, v0
	v_mov_b32_e32 v77, v0
	v_mov_b32_e32 v78, v0
	v_mov_b32_e32 v79, v0
	v_mov_b32_e32 v80, v0
	v_mov_b32_e32 v81, v0
	v_mov_b32_e32 v90, v0
	v_mov_b32_e32 v91, v0
	v_mov_b32_e32 v92, v0
	v_mov_b32_e32 v93, v0
	v_mov_b32_e32 v94, v0
	v_mov_b32_e32 v95, v0
	v_mov_b32_e32 v96, v0
	v_mov_b32_e32 v97, v0
	v_mov_b32_e32 v106, v0
	v_mov_b32_e32 v107, v0
	v_mov_b32_e32 v108, v0
	v_mov_b32_e32 v109, v0
	v_mov_b32_e32 v110, v0
	v_mov_b32_e32 v111, v0
	v_mov_b32_e32 v112, v0
	v_mov_b32_e32 v113, v0
	v_mov_b32_e32 v126, v0
	v_mov_b32_e32 v127, v0
	v_mov_b32_e32 v128, v0
	v_mov_b32_e32 v129, v0
	v_mov_b32_e32 v134, v0
	v_mov_b32_e32 v135, v0
	v_mov_b32_e32 v136, v0
	v_mov_b32_e32 v137, v0
	.p2alignl 6, 3212836864

.LBB0_1410:
	s_ashr_i32 s43, s42, 31
	s_lshl_b64 s[20:21], s[42:43], 19
	s_add_u32 s48, s16, s20
	s_addc_u32 s49, s17, s21
	s_and_b64 s[20:21], s[46:47], exec
	s_cselect_b32 s33, s49, s53
	s_cselect_b32 s39, s48, s52
	s_ashr_i32 s45, s44, 31
	s_lshl_b64 s[20:21], s[44:45], 19
	s_add_u32 s50, s8, s20
	s_addc_u32 s51, s9, s21
	s_and_b64 s[20:21], s[46:47], exec
	s_cselect_b32 s43, s51, s55
	s_cselect_b32 s45, s50, s54
	s_add_u32 s52, s52, 0x40080
	s_addc_u32 s53, s53, 0
	s_add_u32 s65, s54, 0x100
	v_mov_b32_e32 v0, 0
	s_addc_u32 s66, s55, 0
	s_mov_b32 s67, -2
	v_mov_b32_e32 v1, v0
	v_mov_b32_e32 v2, v0
	v_mov_b32_e32 v3, v0
	v_mov_b32_e32 v4, v0
	v_mov_b32_e32 v5, v0
	v_mov_b32_e32 v6, v0
	v_mov_b32_e32 v7, v0
	v_mov_b32_e32 v16, v0
	v_mov_b32_e32 v17, v0
	v_mov_b32_e32 v18, v0
	v_mov_b32_e32 v19, v0
	v_mov_b32_e32 v20, v0
	v_mov_b32_e32 v21, v0
	v_mov_b32_e32 v22, v0
	v_mov_b32_e32 v23, v0
	v_mov_b32_e32 v32, v0
	v_mov_b32_e32 v33, v0
	v_mov_b32_e32 v34, v0
	v_mov_b32_e32 v35, v0
	v_mov_b32_e32 v36, v0
	v_mov_b32_e32 v37, v0
	v_mov_b32_e32 v38, v0
	v_mov_b32_e32 v39, v0
	v_mov_b32_e32 v50, v0
	v_mov_b32_e32 v51, v0
	v_mov_b32_e32 v52, v0
	v_mov_b32_e32 v53, v0
	v_mov_b32_e32 v54, v0
	v_mov_b32_e32 v55, v0
	v_mov_b32_e32 v56, v0
	v_mov_b32_e32 v57, v0
	v_mov_b32_e32 v8, v0
	v_mov_b32_e32 v9, v0
	v_mov_b32_e32 v10, v0
	v_mov_b32_e32 v11, v0
	v_mov_b32_e32 v12, v0
	v_mov_b32_e32 v13, v0
	v_mov_b32_e32 v14, v0
	v_mov_b32_e32 v15, v0
	v_mov_b32_e32 v24, v0
	v_mov_b32_e32 v25, v0
	v_mov_b32_e32 v26, v0
	v_mov_b32_e32 v27, v0
	v_mov_b32_e32 v28, v0
	v_mov_b32_e32 v29, v0
	v_mov_b32_e32 v30, v0
	v_mov_b32_e32 v31, v0
	v_mov_b32_e32 v40, v0
	v_mov_b32_e32 v41, v0
	v_mov_b32_e32 v42, v0
	v_mov_b32_e32 v43, v0
	v_mov_b32_e32 v44, v0
	v_mov_b32_e32 v45, v0
	v_mov_b32_e32 v46, v0
	v_mov_b32_e32 v47, v0
	v_mov_b32_e32 v58, v0
	v_mov_b32_e32 v59, v0
	v_mov_b32_e32 v60, v0
	v_mov_b32_e32 v61, v0
	v_mov_b32_e32 v62, v0
	v_mov_b32_e32 v63, v0
	v_mov_b32_e32 v64, v0
	v_mov_b32_e32 v65, v0
	v_mov_b32_e32 v66, v0
	v_mov_b32_e32 v67, v0
	v_mov_b32_e32 v68, v0
	v_mov_b32_e32 v69, v0
	v_mov_b32_e32 v70, v0
	v_mov_b32_e32 v71, v0
	v_mov_b32_e32 v72, v0
	v_mov_b32_e32 v73, v0
	v_mov_b32_e32 v82, v0
	v_mov_b32_e32 v83, v0
	v_mov_b32_e32 v84, v0
	v_mov_b32_e32 v85, v0
	v_mov_b32_e32 v86, v0
	v_mov_b32_e32 v87, v0
	v_mov_b32_e32 v88, v0
	v_mov_b32_e32 v89, v0
	v_mov_b32_e32 v98, v0
	v_mov_b32_e32 v99, v0
	v_mov_b32_e32 v100, v0
	v_mov_b32_e32 v101, v0
	v_mov_b32_e32 v102, v0
	v_mov_b32_e32 v103, v0
	v_mov_b32_e32 v104, v0
	v_mov_b32_e32 v105, v0
	v_mov_b32_e32 v114, v0
	v_mov_b32_e32 v115, v0
	v_mov_b32_e32 v116, v0
	v_mov_b32_e32 v117, v0
	v_mov_b32_e32 v118, v0
	v_mov_b32_e32 v119, v0
	v_mov_b32_e32 v120, v0
	v_mov_b32_e32 v121, v0
	v_mov_b32_e32 v74, v0
	v_mov_b32_e32 v75, v0
	v_mov_b32_e32 v76, v0
	v_mov_b32_e32 v77, v0
	v_mov_b32_e32 v78, v0
	v_mov_b32_e32 v79, v0
	v_mov_b32_e32 v80, v0
	v_mov_b32_e32 v81, v0
	v_mov_b32_e32 v90, v0
	v_mov_b32_e32 v91, v0
	v_mov_b32_e32 v92, v0
	v_mov_b32_e32 v93, v0
	v_mov_b32_e32 v94, v0
	v_mov_b32_e32 v95, v0
	v_mov_b32_e32 v96, v0
	v_mov_b32_e32 v97, v0
	v_mov_b32_e32 v106, v0
	v_mov_b32_e32 v107, v0
	v_mov_b32_e32 v108, v0
	v_mov_b32_e32 v109, v0
	v_mov_b32_e32 v110, v0
	v_mov_b32_e32 v111, v0
	v_mov_b32_e32 v112, v0
	v_mov_b32_e32 v113, v0
	v_mov_b32_e32 v122, v0
	v_mov_b32_e32 v123, v0
	v_mov_b32_e32 v124, v0
	v_mov_b32_e32 v125, v0
	v_mov_b32_e32 v126, v0
	v_mov_b32_e32 v127, v0
	v_mov_b32_e32 v128, v0
	v_mov_b32_e32 v129, v0
	.p2alignl 6, 3212836864

.LBB0_1977:
	s_add_u32 s66, s50, 0x100
	v_mov_b32_e32 v0, 0
	s_addc_u32 s67, s51, 0
	s_mov_b32 s68, -2
	v_mov_b32_e32 v1, v0
	v_mov_b32_e32 v2, v0
	v_mov_b32_e32 v3, v0
	v_mov_b32_e32 v4, v0
	v_mov_b32_e32 v5, v0
	v_mov_b32_e32 v6, v0
	v_mov_b32_e32 v7, v0
	v_mov_b32_e32 v16, v0
	v_mov_b32_e32 v17, v0
	v_mov_b32_e32 v18, v0
	v_mov_b32_e32 v19, v0
	v_mov_b32_e32 v20, v0
	v_mov_b32_e32 v21, v0
	v_mov_b32_e32 v22, v0
	v_mov_b32_e32 v23, v0
	v_mov_b32_e32 v32, v0
	v_mov_b32_e32 v33, v0
	v_mov_b32_e32 v34, v0
	v_mov_b32_e32 v35, v0
	v_mov_b32_e32 v36, v0
	v_mov_b32_e32 v37, v0
	v_mov_b32_e32 v38, v0
	v_mov_b32_e32 v39, v0
	v_mov_b32_e32 v50, v0
	v_mov_b32_e32 v51, v0
	v_mov_b32_e32 v52, v0
	v_mov_b32_e32 v53, v0
	v_mov_b32_e32 v54, v0
	v_mov_b32_e32 v55, v0
	v_mov_b32_e32 v56, v0
	v_mov_b32_e32 v57, v0
	v_mov_b32_e32 v8, v0
	v_mov_b32_e32 v9, v0
	v_mov_b32_e32 v10, v0
	v_mov_b32_e32 v11, v0
	v_mov_b32_e32 v12, v0
	v_mov_b32_e32 v13, v0
	v_mov_b32_e32 v14, v0
	v_mov_b32_e32 v15, v0
	v_mov_b32_e32 v24, v0
	v_mov_b32_e32 v25, v0
	v_mov_b32_e32 v26, v0
	v_mov_b32_e32 v27, v0
	v_mov_b32_e32 v28, v0
	v_mov_b32_e32 v29, v0
	v_mov_b32_e32 v30, v0
	v_mov_b32_e32 v31, v0
	v_mov_b32_e32 v40, v0
	v_mov_b32_e32 v41, v0
	v_mov_b32_e32 v42, v0
	v_mov_b32_e32 v43, v0
	v_mov_b32_e32 v44, v0
	v_mov_b32_e32 v45, v0
	v_mov_b32_e32 v46, v0
	v_mov_b32_e32 v47, v0
	v_mov_b32_e32 v58, v0
	v_mov_b32_e32 v59, v0
	v_mov_b32_e32 v60, v0
	v_mov_b32_e32 v61, v0
	v_mov_b32_e32 v62, v0
	v_mov_b32_e32 v63, v0
	v_mov_b32_e32 v64, v0
	v_mov_b32_e32 v65, v0
	v_mov_b32_e32 v66, v0
	v_mov_b32_e32 v67, v0
	v_mov_b32_e32 v68, v0
	v_mov_b32_e32 v69, v0
	v_mov_b32_e32 v70, v0
	v_mov_b32_e32 v71, v0
	v_mov_b32_e32 v72, v0
	v_mov_b32_e32 v73, v0
	v_mov_b32_e32 v82, v0
	v_mov_b32_e32 v83, v0
	v_mov_b32_e32 v84, v0
	v_mov_b32_e32 v85, v0
	v_mov_b32_e32 v86, v0
	v_mov_b32_e32 v87, v0
	v_mov_b32_e32 v88, v0
	v_mov_b32_e32 v89, v0
	v_mov_b32_e32 v98, v0
	v_mov_b32_e32 v99, v0
	v_mov_b32_e32 v100, v0
	v_mov_b32_e32 v101, v0
	v_mov_b32_e32 v102, v0
	v_mov_b32_e32 v103, v0
	v_mov_b32_e32 v104, v0
	v_mov_b32_e32 v105, v0
	v_mov_b32_e32 v114, v0
	v_mov_b32_e32 v115, v0
	v_mov_b32_e32 v116, v0
	v_mov_b32_e32 v117, v0
	v_mov_b32_e32 v118, v0
	v_mov_b32_e32 v119, v0
	v_mov_b32_e32 v120, v0
	v_mov_b32_e32 v121, v0
	v_mov_b32_e32 v74, v0
	v_mov_b32_e32 v75, v0
	v_mov_b32_e32 v76, v0
	v_mov_b32_e32 v77, v0
	v_mov_b32_e32 v78, v0
	v_mov_b32_e32 v79, v0
	v_mov_b32_e32 v80, v0
	v_mov_b32_e32 v81, v0
	v_mov_b32_e32 v90, v0
	v_mov_b32_e32 v91, v0
	v_mov_b32_e32 v92, v0
	v_mov_b32_e32 v93, v0
	v_mov_b32_e32 v94, v0
	v_mov_b32_e32 v95, v0
	v_mov_b32_e32 v96, v0
	v_mov_b32_e32 v97, v0
	v_mov_b32_e32 v106, v0
	v_mov_b32_e32 v107, v0
	v_mov_b32_e32 v108, v0
	v_mov_b32_e32 v109, v0
	v_mov_b32_e32 v110, v0
	v_mov_b32_e32 v111, v0
	v_mov_b32_e32 v112, v0
	v_mov_b32_e32 v113, v0
	v_mov_b32_e32 v126, v0
	v_mov_b32_e32 v127, v0
	v_mov_b32_e32 v128, v0
	v_mov_b32_e32 v129, v0
	v_mov_b32_e32 v134, v0
	v_mov_b32_e32 v135, v0
	v_mov_b32_e32 v136, v0
	v_mov_b32_e32 v137, v0
	.p2alignl 6, 3212836864
